# attention units 2-4: the inter-unit workgroup barrier moved from before the next unit's first global loads to directly before its first LDS write (loads in flight while waiting)
# baseline (speedup 1.0000x reference)
; __device__ __forceinline__ unsigned cvtpk(float lo, float hi) { f32x2_t v = {lo, hi}; bf16x2_t b = __builtin_convertvector(v, bf16x2_t); return __builtin_bit_cast(unsigned, b); }
; #define SB_LD(t, KR, VR) do { KR = *(const v4u*)(kg + (size_t)(t) * 64 * DH); VR = *(const v4u*)(vg + (size_t)(t) * 64 * DH); } while (0)
; __device__ __forceinline__ void unit_sb(const bf16* Q, const bf16* K, const bf16* V, bf16* O, int b, int h, int qb, LAS unsigned char* lds) {
;     ...
;     { v4u k3, v3, k2, v2, k1, v1, k0, v0;
;       SB_LD(T0 + 3, k3, v3); SB_LD(T0 + 2, k2, v2); SB_LD(T0 + 1, k1, v1); SB_LD(T0, k0, v0);
;       if (T0 >= 1) SB_LD(T0 - 1, kA, vA); if (T0 >= 2) SB_LD(T0 - 2, kB, vB);
;     ...
;     bf16* op = O + (rowbase + qw0 + r32) * DH + h * HD + 4 * hi;
; #pragma unroll
;     for (int g = 0; g < 4; ++g) { u32x2 w0, w1; w0.x = cvtpk(o0[4 * g], o0[4 * g + 1]); w0.y = cvtpk(o0[4 * g + 2], o0[4 * g + 3]);
;         w1.x = cvtpk(o1[4 * g], o1[4 * g + 1]); w1.y = cvtpk(o1[4 * g + 2], o1[4 * g + 3]);
;         *(u32x2*)(op + 8 * g) = w0; *(u32x2*)(op + 32 + 8 * g) = w1; }
.LBB0_406:
	v_lshlrev_b32_e32 v2, 1, v140
	v_lshl_add_u64 v[36:37], v[166:167], 0, v[2:3]
	v_cvt_pk_bf16_f32 v20, v20, v21
	v_cvt_pk_bf16_f32 v21, v22, v23
	v_cvt_pk_bf16_f32 v4, v4, v5
	v_cvt_pk_bf16_f32 v5, v6, v7
	global_store_dwordx2 v[36:37], v[20:21], off
	global_store_dwordx2 v[36:37], v[4:5], off offset:64
	v_cvt_pk_bf16_f32 v4, v24, v25
	v_cvt_pk_bf16_f32 v5, v26, v27
	v_cvt_pk_bf16_f32 v6, v8, v9
	v_cvt_pk_bf16_f32 v7, v10, v11
	s_lshl_b32 s86, s43, 2
	global_store_dwordx2 v[36:37], v[4:5], off offset:16
	global_store_dwordx2 v[36:37], v[6:7], off offset:80
	v_cvt_pk_bf16_f32 v4, v28, v29
	v_cvt_pk_bf16_f32 v5, v30, v31
	v_cvt_pk_bf16_f32 v6, v12, v13
	v_cvt_pk_bf16_f32 v7, v14, v15
	s_or_b32 s18, s86, 3
	global_store_dwordx2 v[36:37], v[4:5], off offset:32
	global_store_dwordx2 v[36:37], v[6:7], off offset:96
	v_cvt_pk_bf16_f32 v4, v32, v33
	v_cvt_pk_bf16_f32 v5, v34, v35
	v_cvt_pk_bf16_f32 v6, v16, v17
	v_cvt_pk_bf16_f32 v7, v18, v19
	s_lshl_b32 s92, s18, 16
	s_or_b32 s17, s86, 2
	global_store_dwordx2 v[36:37], v[4:5], off offset:48
	global_store_dwordx2 v[36:37], v[6:7], off offset:112
	v_lshl_add_u64 v[4:5], v[136:137], 0, s[92:93]
	v_lshl_add_u64 v[6:7], v[164:165], 0, s[92:93]
	s_lshl_b32 s92, s17, 16
	s_or_b32 s2, s86, 1
	global_load_dwordx4 v[32:35], v[4:5], off
	global_load_dwordx4 v[28:31], v[6:7], off
	v_lshl_add_u64 v[4:5], v[136:137], 0, s[92:93]
	v_lshl_add_u64 v[6:7], v[164:165], 0, s[92:93]
	s_lshl_b32 s92, s2, 16
	global_load_dwordx4 v[24:27], v[4:5], off
	global_load_dwordx4 v[20:23], v[6:7], off
	v_lshl_add_u64 v[4:5], v[136:137], 0, s[92:93]
	v_lshl_add_u64 v[6:7], v[164:165], 0, s[92:93]
	s_lshl_b32 s92, s43, 18
	global_load_dwordx4 v[16:19], v[4:5], off
	global_load_dwordx4 v[12:15], v[6:7], off
	v_lshl_add_u64 v[4:5], v[136:137], 0, s[92:93]
	v_lshl_add_u64 v[6:7], v[164:165], 0, s[92:93]
	global_load_dwordx4 v[8:11], v[4:5], off
	s_nop 0
	global_load_dwordx4 v[4:7], v[6:7], off
	s_cmp_lg_u32 s43, 0
	s_cselect_b64 s[0:1], -1, 0
	s_cmp_eq_u32 s43, 0
	v_readfirstlane_b32 s3, v0
	s_cbranch_scc1 .LBB0_408
	s_add_i32 s92, s86, -1
	s_lshl_b64 s[10:11], s[92:93], 16
	v_lshl_add_u64 v[36:37], v[136:137], 0, s[10:11]
	v_lshl_add_u64 v[38:39], v[164:165], 0, s[10:11]
	global_load_dwordx4 v[70:73], v[36:37], off
	global_load_dwordx4 v[74:77], v[38:39], off

; #define LAS __attribute__((address_space(3)))
; #define SB_WR(t, KR, VR) do { int wo_ = ((t) % 5) * BUF_BYTES; asm volatile("" : "+s"(wo_)); LAS unsigned char* bb_ = lds + wo_; *(LAS v4u*)(bb_ + BUF_K + (skey * KP + sch * 8) * 2) = KR; *(LAS v4u*)(bb_ + BUF_V + (skey * VP + sch * 8) * 2) = VR; } while (0)
; __device__ __forceinline__ void unit_sb(const bf16* Q, const bf16* K, const bf16* V, bf16* O, int b, int h, int qb, LAS unsigned char* lds) {
;     ...
;       SB_WR(T0 + 3, k3, v3); SB_WR(T0 + 2, k2, v2); SB_WR(T0 + 1, k1, v1); SB_WR(T0, k0, v0); }
;     f32x16 o0 = {}, o1 = {};
;     float carry = 1.0f, mrun = 0.f, lrun = 0.f;
;     LAS unsigned* alive = (LAS unsigned*)(lds + 5 * BUF_BYTES);
;     __syncthreads();
;     bool done = false; const int NS = T0 + 4;
.LBB0_410:
	s_lshr_b32 s1, s3, 6
	s_lshl_b32 s0, s43, 8
	s_lshl_b32 s10, s1, 5
	v_writelane_b32 v246, s0, 40
	s_add_i32 s85, s10, s0
	v_readlane_b32 s0, v246, 18
	s_and_b32 s0, s0, 3
	s_lshr_b32 s74, s3, 7
	v_writelane_b32 v246, s0, 41
	s_lshl_b32 s3, s0, 2
	s_lshl_b32 s16, s0, 8
	s_mul_i32 s84, s0, 0x17400
	s_add_i32 s0, s3, -4
	s_add_i32 s77, s3, -2
	s_add_i32 s33, s3, -1
	v_readlane_b32 s12, v246, 33
	v_readlane_b32 s13, v246, 34
	s_add_u32 s11, s12, s85
	s_addc_u32 s12, s13, 0
	v_mov_b32_e32 v37, s12
	v_or_b32_e32 v36, s11, v146
	v_lshlrev_b64 v[36:37], 10, v[36:37]
	v_readlane_b32 s11, v246, 28
	v_lshl_add_u64 v[36:37], s[14:15], 0, v[36:37]
	s_lshl_b32 s12, s11, 1
	s_mov_b32 s13, s93
	v_lshl_add_u64 v[166:167], v[36:37], 0, s[12:13]
	v_mov_b32_e32 v161, v3
	v_lshl_add_u64 v[36:37], v[166:167], 0, v[160:161]
	global_load_dwordx4 v[86:89], v[36:37], off
	global_load_dwordx4 v[90:93], v[36:37], off offset:32
	global_load_dwordx4 v[94:97], v[36:37], off offset:64
	global_load_dwordx4 v[98:101], v[36:37], off offset:96
	s_mul_i32 s11, s18, 52
	s_lshr_b32 s11, s11, 8
	s_mul_i32 s11, s11, 5
	s_sub_i32 s11, s18, s11
	s_and_b32 s11, s11, 0xff
	s_mulk_i32 s11, 0x5d00
	s_add_i32 s11, s11, 0
	s_barrier
	v_add_u32_e32 v1, s11, v153
	s_waitcnt vmcnt(11)
	ds_write_b128 v1, v[32:35]
	v_add_u32_e32 v1, s11, v155
	s_mul_i32 s11, s17, 52
	s_lshr_b32 s11, s11, 8
	s_mul_i32 s11, s11, 5
	s_sub_i32 s11, s17, s11
	s_and_b32 s11, s11, 0xff
	s_mulk_i32 s11, 0x5d00
	s_waitcnt vmcnt(10)
	ds_write_b128 v1, v[28:31] offset:11264
	s_add_i32 s11, s11, 0
	v_add_u32_e32 v1, s11, v153
	s_waitcnt vmcnt(9)
	ds_write_b128 v1, v[24:27]
	v_add_u32_e32 v1, s11, v155
	s_mul_i32 s11, s2, 52
	s_lshr_b32 s11, s11, 8
	s_mul_i32 s11, s11, 5
	s_sub_i32 s2, s2, s11
	s_and_b32 s2, s2, 0xff
	s_mulk_i32 s2, 0x5d00
	s_waitcnt vmcnt(8)
	ds_write_b128 v1, v[20:23] offset:11264
	s_add_i32 s2, s2, 0
	v_add_u32_e32 v1, s2, v153
	s_waitcnt vmcnt(7)
	ds_write_b128 v1, v[16:19]
	v_add_u32_e32 v1, s2, v155
	s_mul_i32 s2, s86, 52
	s_lshr_b32 s2, s2, 8
	s_mul_i32 s2, s2, 5
	s_sub_i32 s2, s86, s2
	s_mov_b32 s14, s12
	s_and_b32 s2, s2, 0xff
	v_writelane_b32 v246, s14, 42
	s_mulk_i32 s2, 0x5d00
	s_waitcnt vmcnt(6)
	ds_write_b128 v1, v[12:15] offset:11264
	v_writelane_b32 v246, s15, 43
	s_lshl_b32 s1, s1, 2
	s_mul_i32 s79, s74, 0x5d00
	v_writelane_b32 v246, s18, 44
	s_add_i32 s2, s2, 0
	s_add_i32 s78, s1, 0
	s_add_i32 s1, s84, s79
	v_writelane_b32 v246, s17, 45
	v_add_u32_e32 v1, s2, v153
	s_addk_i32 s1, 0xa300
	s_waitcnt vmcnt(5)
	ds_write_b128 v1, v[8:11]
	v_add_u32_e32 v1, s2, v155
	v_writelane_b32 v246, s1, 28
	s_lshl_b32 s1, s74, 6
	v_mov_b32_e32 v18, v3
	v_mov_b32_e32 v19, v3
	s_waitcnt vmcnt(4)
	ds_write_b128 v1, v[4:7] offset:11264
	s_add_i32 s83, s74, s3
	s_add_i32 s2, s16, s1
	v_add_u32_e32 v1, s10, v208
	v_mov_b32_e32 v4, v3
	v_mov_b32_e32 v5, v3
	v_mov_b32_e32 v6, v3
	v_mov_b32_e32 v7, v3
	v_mov_b32_e32 v8, v3
	v_mov_b32_e32 v9, v3
	v_mov_b32_e32 v10, v3
	v_mov_b32_e32 v11, v3
	v_mov_b32_e32 v12, v3
	v_mov_b32_e32 v13, v3
	v_mov_b32_e32 v14, v3
	v_mov_b32_e32 v15, v3
	v_mov_b32_e32 v16, v3
	v_mov_b32_e32 v17, v3
	v_mov_b64_e32 v[34:35], v[18:19]
	s_mov_b32 s76, 2
	s_add_i32 s43, s86, 4
	s_or_b32 s91, s85, 31
	s_add_i32 s78, s78, 0x1d100
	s_add_i32 s81, s83, -1
	s_add_i32 s82, s2, -1
	v_subrev_u32_e32 v69, s1, v1
	v_mov_b32_e32 v169, 1.0
	s_mov_b32 s80, 0
	v_mov_b64_e32 v[32:33], v[16:17]
	v_mov_b64_e32 v[30:31], v[14:15]
	v_mov_b64_e32 v[28:29], v[12:13]
	v_mov_b64_e32 v[26:27], v[10:11]
	v_mov_b64_e32 v[24:25], v[8:9]
	v_mov_b64_e32 v[22:23], v[6:7]
	v_mov_b64_e32 v[20:21], v[4:5]
	s_waitcnt lgkmcnt(0)
	s_barrier
	v_writelane_b32 v246, s16, 46
	s_branch .LBB0_412

; __device__ __forceinline__ unsigned cvtpk(float lo, float hi) { f32x2_t v = {lo, hi}; bf16x2_t b = __builtin_convertvector(v, bf16x2_t); return __builtin_bit_cast(unsigned, b); }
; #define ATT_LOAD2(t, KR, VR, BR) do { KR = *(const v4u*)(kg + (size_t)(t) * 64 * DH); VR = *(const v4u*)(vg + (size_t)(t) * 64 * DH); if (MODE == 1 && tid < 64) BR = fg[(t) * 64 + tid]; } while (0)
; template <int MODE>
; __device__ __forceinline__ void unit64(const bf16* Q, const bf16* K, const bf16* V, bf16* O, const float* FC, const float* gq, const float* gk, int b, int h, int qb, LAS unsigned char* lds) {
;     ...
;     const int skey = tid >> 3, sch = tid & 7;
;     const bf16* kg = K + (rowbase + skey) * DH + h * HD + sch * 8; const bf16* vg = V + (rowbase + skey) * DH + h * HD + sch * 8;
;     const float* fg = FC + (size_t)(b * NH + h) * SEQ;
;     v4u kreg, vreg; float breg = 0.f; v4u kregB, vregB; float bregB = 0.f;
;     ...
;     ATT_LOAD2(NT - 1, kreg, vreg, breg); ATT_LOAD2(NT - 2, kregB, vregB, bregB);
;     float fq0 = 0.f; if (MODE == 1) fq0 = fg[qw0 + r32];
; __device__ __forceinline__ void unit_sb(const bf16* Q, const bf16* K, const bf16* V, bf16* O, int b, int h, int qb, LAS unsigned char* lds) {
;     ...
;     bf16* op = O + (rowbase + qw0 + r32) * DH + h * HD + 4 * hi;
; #pragma unroll
;     for (int g = 0; g < 4; ++g) { u32x2 w0, w1; w0.x = cvtpk(o0[4 * g], o0[4 * g + 1]); w0.y = cvtpk(o0[4 * g + 2], o0[4 * g + 3]);
;         w1.x = cvtpk(o1[4 * g], o1[4 * g + 1]); w1.y = cvtpk(o1[4 * g + 2], o1[4 * g + 3]);
;         *(u32x2*)(op + 8 * g) = w0; *(u32x2*)(op + 32 + 8 * g) = w1; }
.LBB0_437:
	v_lshl_add_u64 v[36:37], v[166:167], 0, v[2:3]
	v_cvt_pk_bf16_f32 v4, v4, v5
	v_cvt_pk_bf16_f32 v5, v6, v7
	v_cvt_pk_bf16_f32 v6, v20, v21
	v_cvt_pk_bf16_f32 v7, v22, v23
	global_store_dwordx2 v[36:37], v[4:5], off
	global_store_dwordx2 v[36:37], v[6:7], off offset:64
	v_cvt_pk_bf16_f32 v4, v8, v9
	v_cvt_pk_bf16_f32 v5, v10, v11
	v_cvt_pk_bf16_f32 v6, v24, v25
	v_cvt_pk_bf16_f32 v7, v26, v27
	global_store_dwordx2 v[36:37], v[4:5], off offset:16
	global_store_dwordx2 v[36:37], v[6:7], off offset:80
	v_cvt_pk_bf16_f32 v4, v12, v13
	v_cvt_pk_bf16_f32 v5, v14, v15
	v_cvt_pk_bf16_f32 v6, v28, v29
	v_cvt_pk_bf16_f32 v7, v30, v31
	global_store_dwordx2 v[36:37], v[4:5], off offset:32
	global_store_dwordx2 v[36:37], v[6:7], off offset:96
	v_cvt_pk_bf16_f32 v4, v16, v17
	v_cvt_pk_bf16_f32 v5, v18, v19
	v_readlane_b32 s0, v246, 12
	v_cvt_pk_bf16_f32 v6, v32, v33
	v_cvt_pk_bf16_f32 v7, v34, v35
	global_store_dwordx2 v[36:37], v[4:5], off offset:48
	global_store_dwordx2 v[36:37], v[6:7], off offset:112
	v_lshlrev_b64 v[4:5], 1, v[134:135]
	v_readlane_b32 s1, v246, 13
	v_readlane_b32 s14, v246, 23
	s_lshl_b32 s10, s14, 3
	v_lshl_add_u64 v[6:7], s[0:1], 0, v[4:5]
	v_readlane_b32 s0, v246, 8
	v_readlane_b32 s1, v246, 9
	v_readlane_b32 s90, v246, 42
	v_readlane_b32 s91, v246, 43
	v_lshl_add_u64 v[4:5], s[0:1], 0, v[4:5]
	v_readlane_b32 s0, v246, 27
	s_or_b32 s0, s10, s0
	s_ashr_i32 s1, s0, 31
	s_lshl_b64 s[0:1], s[0:1], 13
	v_readlane_b32 s2, v247, 51
	s_mov_b32 s91, s93
	s_add_u32 s0, s2, s0
	v_readlane_b32 s2, v247, 52
	v_lshl_add_u64 v[6:7], v[6:7], 0, s[90:91]
	v_mov_b32_e32 v157, v3
	s_addc_u32 s1, s2, s1
	v_readlane_b32 s2, v246, 29
	v_lshl_add_u64 v[166:167], v[6:7], 0, v[156:157]
	v_lshl_add_u64 v[4:5], v[4:5], 0, s[90:91]
	s_lshl_b32 s92, s2, 1
	v_lshl_add_u64 v[168:169], v[4:5], 0, v[156:157]
	v_lshl_add_u64 v[4:5], v[166:167], 0, s[92:93]
	v_lshl_add_u64 v[6:7], v[168:169], 0, s[92:93]
	global_load_dwordx4 v[74:77], v[4:5], off
	global_load_dwordx4 v[78:81], v[6:7], off
	v_readlane_b32 s15, v246, 24
	v_readfirstlane_b32 s11, v0
	v_mov_b32_e32 v161, 0
	v_mov_b32_e32 v180, 0
	s_and_saveexec_b64 s[2:3], s[8:9]
	s_cbranch_execz .LBB0_439
	v_readlane_b32 s12, v246, 35
	s_nop 1
	v_lshl_or_b32 v1, s12, 8, v206
	global_load_dword v180, v1, s[0:1]

; #define LAS __attribute__((address_space(3)))
; __device__ __forceinline__ unsigned f2bf(float f) { unsigned u = __builtin_bit_cast(unsigned, f); return (u + 0x7fffu + ((u >> 16) & 1u)) >> 16; }
; __device__ __forceinline__ float bf2f(unsigned b) { return __uint_as_float(b << 16); }
; __device__ __forceinline__ float bflo(unsigned w) { return __uint_as_float(w << 16); }
; __device__ __forceinline__ float bfhi(unsigned w) { return __uint_as_float(w & 0xffff0000u); }
; __device__ __forceinline__ float bflo(unsigned w) { return __uint_as_float(w << 16); }
; __device__ __forceinline__ float bfhi(unsigned w) { return __uint_as_float(w & 0xffff0000u); }
; template <int MODE>
; __device__ __forceinline__ void unit64(const bf16* Q, const bf16* K, const bf16* V, bf16* O, const float* FC, const float* gq, const float* gk, int b, int h, int qb, LAS unsigned char* lds) {
;     ...
;     { const bf16* qp = Q + (rowbase + qw0 + r32) * DH + h * HD + 8 * hi;
; #pragma unroll
;       for (int d0 = 0; d0 < 4; ++d0) { v4u w = *(const v4u*)(qp + 16 * d0);
;           if (MODE == 1) { const float* g1 = gq + 16 * d0 + 8 * hi; const float* g2 = gk + 16 * d0 + 8 * hi;
; #pragma unroll
;               for (int j = 0; j < 8; ++j) gmax = fmaxf(gmax, __builtin_fabsf(g1[j] * g2[j]));
;               w.x = cvtpk(bflo(w.x) * g1[0] * g2[0], bfhi(w.x) * g1[1] * g2[1]); w.y = cvtpk(bflo(w.y) * g1[2] * g2[2], bfhi(w.y) * g1[3] * g2[3]);
;               w.z = cvtpk(bflo(w.z) * g1[4] * g2[4], bfhi(w.z) * g1[5] * g2[5]); w.w = cvtpk(bflo(w.w) * g1[6] * g2[6], bfhi(w.w) * g1[7] * g2[7]); }
;           qf[d0] = __builtin_bit_cast(bf16x8, w); } }
;     f32x16 o0 = {}, o1 = {};
;     float carry = 1.0f, mrun = -1e30f, lrun = 0.f;
;     if (MODE == 1) { gmax = fmaxf(gmax, other_half(gmax, hi));
;         mrun = -fq0 * LOG2E + 64.0f * 1.02f * C2 * gmax + 0.5f;
;         { const float c = -mrun; const unsigned ch = f2bf(c); const float r1 = c - bf2f((bf16)ch); const unsigned cm = f2bf(r1); const unsigned cl = f2bf(r1 - bf2f((bf16)cm));
;           u32x4 w = {0x3F803F80u, 0x3F80u | (ch << 16), cm | (cl << 16), 0u}; if (hi) w = u32x4{0u, 0u, 0u, 0u}; qf[4] = __builtin_bit_cast(bf16x8, w); } }
;     else qf[4] = qf[3];
;     LAS unsigned* alive = (LAS unsigned*)(lds + 2 * BUF_BYTES);
;     ...
;     ATT_WRITE2(0, kreg, vreg, breg); __syncthreads();
.LBB0_441:
	s_or_b64 exec, exec, s[2:3]
	s_lshr_b32 s2, s11, 1
	s_and_b32 s11, s2, 0x7fffffe0
	s_add_i32 s33, s11, s16
	v_readlane_b32 s2, v246, 33
	v_or_b32_e32 v2, s33, v146
	v_readlane_b32 s3, v246, 34
	s_add_u32 s2, s2, s33
	v_lshl_add_u64 v[4:5], v[2:3], 2, s[0:1]
	s_addc_u32 s3, s3, 0
	global_load_dword v65, v[4:5], off
	v_mov_b32_e32 v5, s3
	v_or_b32_e32 v4, s2, v146
	v_readlane_b32 s2, v246, 6
	v_lshlrev_b64 v[4:5], 10, v[4:5]
	v_readlane_b32 s3, v246, 7
	s_mov_b32 s91, s93
	v_mov_b32_e32 v151, v3
	v_lshl_add_u64 v[4:5], s[2:3], 0, v[4:5]
	v_lshl_add_u64 v[170:171], v[4:5], 0, s[90:91]
	v_lshl_add_u64 v[56:57], v[170:171], 0, v[150:151]
	global_load_dwordx4 v[12:15], v[56:57], off
	global_load_dwordx4 v[4:7], v[142:143], off offset:16
	global_load_dwordx4 v[16:19], v[142:143], off
	global_load_dwordx4 v[8:11], v[144:145], off offset:16
	global_load_dwordx4 v[48:51], v[144:145], off
	v_add_u32_e32 v157, 0, v155
	s_waitcnt vmcnt(0)
	v_pk_mul_f32 v[20:21], v[16:17], v[48:49]
	s_nop 0
	v_max3_f32 v1, |v20|, 0, |v21|
	v_pk_mul_f32 v[20:21], v[18:19], v[50:51]
	s_nop 0
	v_max3_f32 v1, v1, |v20|, |v21|
	v_pk_mul_f32 v[20:21], v[4:5], v[8:9]
	s_nop 0
	v_max3_f32 v1, v1, |v20|, |v21|
	v_pk_mul_f32 v[20:21], v[6:7], v[10:11]
	s_nop 0
	v_max3_f32 v1, v1, |v20|, |v21|
	global_load_dwordx4 v[28:31], v[56:57], off offset:32
	global_load_dwordx4 v[20:23], v[142:143], off offset:80
	global_load_dwordx4 v[32:35], v[142:143], off offset:64
	global_load_dwordx4 v[24:27], v[144:145], off offset:80
	global_load_dwordx4 v[94:97], v[144:145], off offset:64
	s_waitcnt vmcnt(0)
	v_pk_mul_f32 v[36:37], v[32:33], v[94:95]
	s_nop 0
	v_max3_f32 v1, v1, |v36|, |v37|
	v_pk_mul_f32 v[36:37], v[34:35], v[96:97]
	s_nop 0
	v_max3_f32 v1, v1, |v36|, |v37|
	v_pk_mul_f32 v[36:37], v[20:21], v[24:25]
	s_nop 0
	v_max3_f32 v1, v1, |v36|, |v37|
	v_pk_mul_f32 v[36:37], v[22:23], v[26:27]
	s_nop 0
	v_max3_f32 v1, v1, |v36|, |v37|
	global_load_dwordx4 v[44:47], v[56:57], off offset:64
	global_load_dwordx4 v[36:39], v[142:143], off offset:144
	global_load_dwordx4 v[52:55], v[142:143], off offset:128
	global_load_dwordx4 v[40:43], v[144:145], off offset:144
	global_load_dwordx4 v[98:101], v[144:145], off offset:128
	s_waitcnt vmcnt(0)
	v_pk_mul_f32 v[58:59], v[52:53], v[98:99]
	s_nop 0
	v_max3_f32 v1, v1, |v58|, |v59|
	v_pk_mul_f32 v[58:59], v[54:55], v[100:101]
	s_nop 0
	v_max3_f32 v1, v1, |v58|, |v59|
	v_pk_mul_f32 v[58:59], v[36:37], v[40:41]
	s_nop 0
	v_max3_f32 v1, v1, |v58|, |v59|
	v_pk_mul_f32 v[58:59], v[38:39], v[42:43]
	s_nop 0
	v_max3_f32 v1, v1, |v58|, |v59|
	global_load_dwordx4 v[70:73], v[56:57], off offset:96
	s_nop 0
	global_load_dwordx4 v[56:59], v[142:143], off offset:208
	global_load_dwordx4 v[102:105], v[142:143], off offset:192
	global_load_dwordx4 v[60:63], v[144:145], off offset:208
	global_load_dwordx4 v[106:109], v[144:145], off offset:192
	s_waitcnt vmcnt(0)
	v_pk_mul_f32 v[66:67], v[102:103], v[106:107]
	s_nop 0
	v_max3_f32 v1, v1, |v66|, |v67|
	v_pk_mul_f32 v[66:67], v[104:105], v[108:109]
	s_nop 0
	v_max3_f32 v1, v1, |v66|, |v67|
	v_pk_mul_f32 v[66:67], v[56:57], v[60:61]
	s_nop 0
	v_max3_f32 v1, v1, |v66|, |v67|
	v_pk_mul_f32 v[66:67], v[58:59], v[62:63]
	s_nop 0
	v_max3_f32 v2, v1, |v66|, |v67|
	v_mov_b32_e32 v64, v2
	v_mov_b32_e32 v110, v2
	s_nop 1
	v_permlane32_swap_b32_e32 v64, v110
	s_barrier
	v_add_u32_e32 v1, 0, v153
	ds_write_b128 v1, v[74:77]
	ds_write_b128 v157, v[78:81] offset:11264
	s_and_saveexec_b64 s[2:3], s[8:9]
	s_cbranch_execz .LBB0_443
	v_mul_f32_e32 v66, 0xbfb8aa3b, v180
	v_bfe_u32 v67, v66, 16, 1
	v_add3_u32 v66, v66, v67, s94
	v_and_b32_e32 v67, 0xffff0000, v66
	s_mov_b32 s12, 0xbfb8aa3b
	v_fma_f32 v67, v180, s12, -v67
	v_bfe_u32 v69, v67, 16, 1
	v_add3_u32 v69, v67, v69, s94
	v_and_b32_e32 v69, 0xffff0000, v69
	v_sub_f32_e32 v67, v67, v69
	v_bfe_u32 v90, v67, 16, 1
	v_add3_u32 v67, v67, v90, s94
	v_or_b32_sdwa v66, v69, v66 dst_sel:DWORD dst_unused:UNUSED_PAD src0_sel:DWORD src1_sel:WORD_1
	v_or_b32_sdwa v67, v67, v212 dst_sel:DWORD dst_unused:UNUSED_PAD src0_sel:WORD_1 src1_sel:DWORD
	v_mov_b32_e32 v69, v3
	ds_write_b128 v211, v[66:69] offset:128
	ds_write_b128 v211, v[216:219] offset:144

; __device__ __forceinline__ unsigned cvtpk(float lo, float hi) { f32x2_t v = {lo, hi}; bf16x2_t b = __builtin_convertvector(v, bf16x2_t); return __builtin_bit_cast(unsigned, b); }
; __device__ __forceinline__ float other_half(float v, int hi) { auto r = __builtin_amdgcn_permlane32_swap(__float_as_uint(v), __float_as_uint(v), false, false); return __uint_as_float(hi ? r[0] : r[1]); }
; #define ATT_LOAD2(t, KR, VR, BR) do { KR = *(const v4u*)(kg + (size_t)(t) * 64 * DH); VR = *(const v4u*)(vg + (size_t)(t) * 64 * DH); if (MODE == 1 && tid < 64) BR = fg[(t) * 64 + tid]; } while (0)
; template <int MODE>
; __device__ __forceinline__ void unit64(const bf16* Q, const bf16* K, const bf16* V, bf16* O, const float* FC, const float* gq, const float* gk, int b, int h, int qb, LAS unsigned char* lds) {
;     ...
;     ATT_LOAD2(NT - 1, kreg, vreg, breg); ATT_LOAD2(NT - 2, kregB, vregB, bregB);
;     ...
;     float inv = 1.0f;
;     if (MODE == 1) { const float lt = lrun + other_half(lrun, hi); inv = 1.0f / lt; }
;     bf16* op = O + (rowbase + qw0 + r32) * DH + h * HD + 4 * hi;
; #pragma unroll
;     for (int g = 0; g < 4; ++g) { u32x2 w0, w1; w0.x = cvtpk(o0[4 * g] * inv, o0[4 * g + 1] * inv); w0.y = cvtpk(o0[4 * g + 2] * inv, o0[4 * g + 3] * inv);
;         w1.x = cvtpk(o1[4 * g] * inv, o1[4 * g + 1] * inv); w1.y = cvtpk(o1[4 * g + 2] * inv, o1[4 * g + 3] * inv);
;         *(u32x2*)(op + 8 * g) = w0; *(u32x2*)(op + 32 + 8 * g) = w1; }
.LBB0_470:
	v_mov_b32_e32 v2, v181
	v_mov_b32_e32 v36, v181
	v_readlane_b32 s10, v246, 14
	s_nop 0
	v_permlane32_swap_b32_e32 v2, v36
	v_readlane_b32 s11, v246, 15
	v_lshlrev_b32_e32 v164, 1, v152
	v_mov_b32_e32 v165, v3
	v_cndmask_b32_e64 v2, v2, v36, s[10:11]
	v_add_f32_e32 v2, v181, v2
	v_div_scale_f32 v36, s[10:11], v2, v2, 1.0
	v_rcp_f32_e32 v37, v36
	v_readlane_b32 s10, v246, 38
	s_lshl_b32 s10, s10, 1
	s_mov_b32 s11, s93
	v_fma_f32 v38, -v36, v37, 1.0
	v_fmac_f32_e32 v37, v38, v37
	v_div_scale_f32 v38, vcc, 1.0, v2, 1.0
	v_mul_f32_e32 v39, v38, v37
	v_fma_f32 v40, -v36, v39, v38
	v_fmac_f32_e32 v39, v40, v37
	v_fma_f32 v36, -v36, v39, v38
	v_div_fmas_f32 v36, v36, v37, v39
	v_div_fixup_f32 v2, v36, v2, 1.0
	v_pk_mul_f32 v[20:21], v[20:21], v[2:3] op_sel_hi:[1,0]
	v_pk_mul_f32 v[22:23], v[22:23], v[2:3] op_sel_hi:[1,0]
	v_pk_mul_f32 v[4:5], v[4:5], v[2:3] op_sel_hi:[1,0]
	v_pk_mul_f32 v[6:7], v[6:7], v[2:3] op_sel_hi:[1,0]
	v_lshl_add_u64 v[36:37], v[170:171], 0, v[164:165]
	v_cvt_pk_bf16_f32 v20, v20, v21
	v_cvt_pk_bf16_f32 v21, v22, v23
	v_cvt_pk_bf16_f32 v4, v4, v5
	v_cvt_pk_bf16_f32 v5, v6, v7
	global_store_dwordx2 v[36:37], v[20:21], off
	global_store_dwordx2 v[36:37], v[4:5], off offset:64
	v_pk_mul_f32 v[4:5], v[24:25], v[2:3] op_sel_hi:[1,0]
	v_pk_mul_f32 v[6:7], v[26:27], v[2:3] op_sel_hi:[1,0]
	v_cvt_pk_bf16_f32 v4, v4, v5
	v_cvt_pk_bf16_f32 v5, v6, v7
	v_pk_mul_f32 v[6:7], v[8:9], v[2:3] op_sel_hi:[1,0]
	v_pk_mul_f32 v[8:9], v[10:11], v[2:3] op_sel_hi:[1,0]
	v_cvt_pk_bf16_f32 v6, v6, v7
	v_cvt_pk_bf16_f32 v7, v8, v9
	global_store_dwordx2 v[36:37], v[4:5], off offset:16
	global_store_dwordx2 v[36:37], v[6:7], off offset:80
	v_pk_mul_f32 v[4:5], v[28:29], v[2:3] op_sel_hi:[1,0]
	v_pk_mul_f32 v[6:7], v[30:31], v[2:3] op_sel_hi:[1,0]
	v_cvt_pk_bf16_f32 v4, v4, v5
	v_cvt_pk_bf16_f32 v5, v6, v7
	v_pk_mul_f32 v[6:7], v[12:13], v[2:3] op_sel_hi:[1,0]
	v_pk_mul_f32 v[8:9], v[14:15], v[2:3] op_sel_hi:[1,0]
	v_cvt_pk_bf16_f32 v6, v6, v7
	v_cvt_pk_bf16_f32 v7, v8, v9
	global_store_dwordx2 v[36:37], v[4:5], off offset:32
	global_store_dwordx2 v[36:37], v[6:7], off offset:96
	v_pk_mul_f32 v[4:5], v[32:33], v[2:3] op_sel_hi:[1,0]
	v_pk_mul_f32 v[6:7], v[34:35], v[2:3] op_sel_hi:[1,0]
	v_cvt_pk_bf16_f32 v4, v4, v5
	v_cvt_pk_bf16_f32 v5, v6, v7
	v_pk_mul_f32 v[6:7], v[16:17], v[2:3] op_sel_hi:[1,0]
	v_pk_mul_f32 v[8:9], v[18:19], v[2:3] op_sel_hi:[1,0]
	v_cvt_pk_bf16_f32 v6, v6, v7
	v_cvt_pk_bf16_f32 v7, v8, v9
	global_store_dwordx2 v[36:37], v[4:5], off offset:48
	global_store_dwordx2 v[36:37], v[6:7], off offset:112
	v_lshl_add_u64 v[4:5], v[166:167], 0, s[10:11]
	v_lshl_add_u64 v[6:7], v[168:169], 0, s[10:11]
	global_load_dwordx4 v[74:77], v[4:5], off
	global_load_dwordx4 v[78:81], v[6:7], off
	v_readfirstlane_b32 s12, v0
	s_waitcnt vmcnt(10)
	v_mov_b32_e32 v161, 0
	v_mov_b32_e32 v165, 0
	s_and_saveexec_b64 s[10:11], s[8:9]
	s_cbranch_execz .LBB0_472
	v_readlane_b32 s13, v246, 44
	s_nop 1
	v_lshl_or_b32 v2, s13, 8, v206
	global_load_dword v165, v2, s[0:1]

; #define LAS __attribute__((address_space(3)))
; __device__ __forceinline__ unsigned f2bf(float f) { unsigned u = __builtin_bit_cast(unsigned, f); return (u + 0x7fffu + ((u >> 16) & 1u)) >> 16; }
; __device__ __forceinline__ float bf2f(unsigned b) { return __uint_as_float(b << 16); }
; __device__ __forceinline__ float bflo(unsigned w) { return __uint_as_float(w << 16); }
; __device__ __forceinline__ float bfhi(unsigned w) { return __uint_as_float(w & 0xffff0000u); }
; __device__ __forceinline__ float bflo(unsigned w) { return __uint_as_float(w << 16); }
; template <int MODE>
; __device__ __forceinline__ void unit64(const bf16* Q, const bf16* K, const bf16* V, bf16* O, const float* FC, const float* gq, const float* gk, int b, int h, int qb, LAS unsigned char* lds) {
;     ...
;     float fq0 = 0.f; if (MODE == 1) fq0 = fg[qw0 + r32];
;     bf16x8 qf[5]; float gmax = 0.f;
;     { const bf16* qp = Q + (rowbase + qw0 + r32) * DH + h * HD + 8 * hi;
; #pragma unroll
;       for (int d0 = 0; d0 < 4; ++d0) { v4u w = *(const v4u*)(qp + 16 * d0);
;           if (MODE == 1) { const float* g1 = gq + 16 * d0 + 8 * hi; const float* g2 = gk + 16 * d0 + 8 * hi;
; #pragma unroll
;               for (int j = 0; j < 8; ++j) gmax = fmaxf(gmax, __builtin_fabsf(g1[j] * g2[j]));
;               w.x = cvtpk(bflo(w.x) * g1[0] * g2[0], bfhi(w.x) * g1[1] * g2[1]); w.y = cvtpk(bflo(w.y) * g1[2] * g2[2], bfhi(w.y) * g1[3] * g2[3]);
;               w.z = cvtpk(bflo(w.z) * g1[4] * g2[4], bfhi(w.z) * g1[5] * g2[5]); w.w = cvtpk(bflo(w.w) * g1[6] * g2[6], bfhi(w.w) * g1[7] * g2[7]); }
;           qf[d0] = __builtin_bit_cast(bf16x8, w); } }
;     f32x16 o0 = {}, o1 = {};
;     float carry = 1.0f, mrun = -1e30f, lrun = 0.f;
;     if (MODE == 1) { gmax = fmaxf(gmax, other_half(gmax, hi));
;         mrun = -fq0 * LOG2E + 64.0f * 1.02f * C2 * gmax + 0.5f;
;         { const float c = -mrun; const unsigned ch = f2bf(c); const float r1 = c - bf2f((bf16)ch); const unsigned cm = f2bf(r1); const unsigned cl = f2bf(r1 - bf2f((bf16)cm));
;           u32x4 w = {0x3F803F80u, 0x3F80u | (ch << 16), cm | (cl << 16), 0u}; if (hi) w = u32x4{0u, 0u, 0u, 0u}; qf[4] = __builtin_bit_cast(bf16x8, w); } }
;     else qf[4] = qf[3];
;     LAS unsigned* alive = (LAS unsigned*)(lds + 2 * BUF_BYTES);
;     ...
;     ATT_WRITE2(0, kreg, vreg, breg); __syncthreads();
.LBB0_474:
	s_or_b64 exec, exec, s[10:11]
	s_lshr_b32 s10, s12, 1
	s_and_b32 s10, s10, 0x7fffffe0
	v_readlane_b32 s11, v246, 40
	s_add_i32 s33, s10, s11
	v_readlane_b32 s12, v246, 33
	v_or_b32_e32 v2, s33, v146
	v_readlane_b32 s13, v246, 34
	s_add_u32 s11, s12, s33
	v_lshl_add_u64 v[56:57], v[2:3], 2, s[0:1]
	s_addc_u32 s0, s13, 0
	v_or_b32_e32 v58, s11, v146
	v_mov_b32_e32 v59, s0
	v_readlane_b32 s0, v246, 6
	v_lshlrev_b64 v[58:59], 10, v[58:59]
	v_readlane_b32 s1, v246, 7
	s_mov_b32 s91, s93
	global_load_dwordx4 v[90:93], v[144:145], off
	global_load_dwordx4 v[94:97], v[142:143], off
	global_load_dwordx4 v[44:47], v[142:143], off offset:16
	global_load_dwordx4 v[48:51], v[144:145], off offset:16
	global_load_dwordx4 v[52:55], v[144:145], off offset:64
	global_load_dwordx4 v[60:63], v[142:143], off offset:64
	global_load_dwordx4 v[28:31], v[142:143], off offset:80
	global_load_dwordx4 v[32:35], v[144:145], off offset:80
	global_load_dwordx4 v[36:39], v[144:145], off offset:128
	global_load_dwordx4 v[40:43], v[142:143], off offset:128
	global_load_dwordx4 v[12:15], v[142:143], off offset:144
	global_load_dwordx4 v[16:19], v[144:145], off offset:144
	global_load_dwordx4 v[20:23], v[144:145], off offset:192
	global_load_dwordx4 v[24:27], v[142:143], off offset:192
	global_load_dwordx4 v[4:7], v[142:143], off offset:208
	global_load_dwordx4 v[8:11], v[144:145], off offset:208
	v_lshl_add_u64 v[58:59], s[0:1], 0, v[58:59]
	v_mov_b32_e32 v151, v3
	v_lshl_add_u64 v[166:167], v[58:59], 0, s[90:91]
	v_lshl_add_u64 v[58:59], v[166:167], 0, v[150:151]
	global_load_dword v65, v[56:57], off
	global_load_dwordx4 v[106:109], v[58:59], off
	global_load_dwordx4 v[102:105], v[58:59], off offset:32
	global_load_dwordx4 v[98:101], v[58:59], off offset:64
	s_nop 0
	global_load_dwordx4 v[56:59], v[58:59], off offset:96
	s_barrier
	s_waitcnt vmcnt(24)
	ds_write_b128 v1, v[74:77]
	s_waitcnt vmcnt(23)
	ds_write_b128 v157, v[78:81] offset:11264
	s_waitcnt vmcnt(19)
	v_pk_mul_f32 v[66:67], v[94:95], v[90:91]
	v_pk_mul_f32 v[72:73], v[96:97], v[92:93]
	v_max3_f32 v2, |v66|, 0, |v67|
	s_waitcnt vmcnt(17)
	v_pk_mul_f32 v[110:111], v[44:45], v[48:49]
	v_max3_f32 v2, v2, |v72|, |v73|
	v_pk_mul_f32 v[112:113], v[46:47], v[50:51]
	v_max3_f32 v2, v2, |v110|, |v111|
	s_waitcnt vmcnt(15)
	v_pk_mul_f32 v[114:115], v[60:61], v[52:53]
	v_max3_f32 v2, v2, |v112|, |v113|
	v_pk_mul_f32 v[116:117], v[62:63], v[54:55]
	v_max3_f32 v2, v2, |v114|, |v115|
	s_waitcnt vmcnt(13)
	v_pk_mul_f32 v[118:119], v[28:29], v[32:33]
	v_max3_f32 v2, v2, |v116|, |v117|
	v_pk_mul_f32 v[120:121], v[30:31], v[34:35]
	v_max3_f32 v2, v2, |v118|, |v119|
	s_waitcnt vmcnt(11)
	v_pk_mul_f32 v[122:123], v[40:41], v[36:37]
	v_max3_f32 v2, v2, |v120|, |v121|
	v_pk_mul_f32 v[124:125], v[42:43], v[38:39]
	v_max3_f32 v2, v2, |v122|, |v123|
	s_waitcnt vmcnt(9)
	v_pk_mul_f32 v[126:127], v[12:13], v[16:17]
	v_max3_f32 v2, v2, |v124|, |v125|
	v_pk_mul_f32 v[128:129], v[14:15], v[18:19]
	v_max3_f32 v2, v2, |v126|, |v127|
	s_waitcnt vmcnt(7)
	v_pk_mul_f32 v[130:131], v[24:25], v[20:21]
	v_max3_f32 v2, v2, |v128|, |v129|
	v_pk_mul_f32 v[132:133], v[26:27], v[22:23]
	v_max3_f32 v2, v2, |v130|, |v131|
	s_waitcnt vmcnt(5)
	v_pk_mul_f32 v[134:135], v[4:5], v[8:9]
	v_max3_f32 v2, v2, |v132|, |v133|
	v_pk_mul_f32 v[136:137], v[6:7], v[10:11]
	v_max3_f32 v2, v2, |v134|, |v135|
	v_max3_f32 v2, v2, |v136|, |v137|
	v_mov_b32_e32 v64, v2
	v_mov_b32_e32 v71, v2
	s_nop 1
	v_permlane32_swap_b32_e32 v64, v71
	s_and_saveexec_b64 s[0:1], s[8:9]
	s_cbranch_execz .LBB0_476
	v_mul_f32_e32 v66, 0xbfb8aa3b, v165
	v_bfe_u32 v67, v66, 16, 1
	v_add3_u32 v66, v66, v67, s94
	v_and_b32_e32 v67, 0xffff0000, v66
	s_mov_b32 s11, 0xbfb8aa3b
	v_fma_f32 v67, v165, s11, -v67
	v_bfe_u32 v69, v67, 16, 1
	v_add3_u32 v69, v67, v69, s94
	v_and_b32_e32 v69, 0xffff0000, v69
	v_sub_f32_e32 v67, v67, v69
	v_bfe_u32 v72, v67, 16, 1
	v_add3_u32 v67, v67, v72, s94
	v_or_b32_sdwa v66, v69, v66 dst_sel:DWORD dst_unused:UNUSED_PAD src0_sel:DWORD src1_sel:WORD_1
	v_or_b32_sdwa v67, v67, v212 dst_sel:DWORD dst_unused:UNUSED_PAD src0_sel:WORD_1 src1_sel:DWORD
	v_mov_b32_e32 v69, v3
	ds_write_b128 v211, v[66:69] offset:128
	ds_write_b128 v211, v[216:219] offset:144
